# v17 + attention unit start no longer drains the previous unit's output stores
# speedup vs baseline: 1.0188x; 1.0043x over previous
; #define LAS __attribute__((address_space(3)))
; __device__ __forceinline__ void load_q(bf16x8 (&qf)[6], const bf16_t* qn, const bf16_t* qr, const float* rp, int hi) {
; #pragma unroll
;     for (int d0 = 0; d0 < 4; ++d0) qf[d0] = *(const bf16x8*)(qn + d0 * 16 + hi * 8);
;     const u32x4 a = *(const u32x4*)(qr + hi * 8), b = *(const u32x4*)(qr + 16 + hi * 8);
;     const f32x4 c0 = *(const f32x4*)(rp + hi * 8), c1 = *(const f32x4*)(rp + hi * 8 + 4), s0 = *(const f32x4*)(rp + 16 + hi * 8), s1 = *(const f32x4*)(rp + 16 + hi * 8 + 4);
;     const float x1[8] = {bflo(a.x), bfhi(a.x), bflo(a.y), bfhi(a.y), bflo(a.z), bfhi(a.z), bflo(a.w), bfhi(a.w)};
;     const float x2[8] = {bflo(b.x), bfhi(b.x), bflo(b.y), bfhi(b.y), bflo(b.z), bfhi(b.z), bflo(b.w), bfhi(b.w)};
;     const float cs[8] = {c0[0], c0[1], c0[2], c0[3], c1[0], c1[1], c1[2], c1[3]}, sn[8] = {s0[0], s0[1], s0[2], s0[3], s1[0], s1[1], s1[2], s1[3]};
;     float o1[8], o2[8];
; #pragma unroll
;     for (int j = 0; j < 8; ++j) { o1[j] = x1[j] * cs[j] - x2[j] * sn[j]; o2[j] = x1[j] * sn[j] + x2[j] * cs[j]; }
;     u32x4 w1 = (u32x4){pk2(o1[0], o1[1]), pk2(o1[2], o1[3]), pk2(o1[4], o1[5]), pk2(o1[6], o1[7])}, w2 = (u32x4){pk2(o2[0], o2[1]), pk2(o2[2], o2[3]), pk2(o2[4], o2[5]), pk2(o2[6], o2[7])};
;     qf[4] = __builtin_bit_cast(bf16x8, w1); qf[5] = __builtin_bit_cast(bf16x8, w2);
; }
; __device__ __forceinline__ void prompt_unit(LAS unsigned char* lds, const Ptrs& P, int qloc0, int qglob0, int kloc0, int kglob0, int h, int qb) {
;     int tid_ = threadIdx.x; asm volatile("" : "+v"(tid_));
;     const int tid = tid_, lane = tid & 63, r32 = lane & 31, hi = lane >> 5; const int wid = __builtin_amdgcn_readfirstlane(tid >> 6);
;     const int NTL = 4 * qb + 4, cq = 4 * qb + (wid >> 1);
;     bf16x8 qf[6];
;     { const int ql = qloc0 + 32 * wid + r32, pos = qb * 256 + 32 * wid + r32;
;       load_q(qf, P.Qn + (size_t)ql * 1024 + h * 64, P.Qr + (size_t)ql * 512 + h * 32, P.rope + pos * 32, hi); }
;     const bf16_t* kn_src = P.Kn + (size_t)(kloc0 + (tid >> 3)) * 1024 + h * 64 + (tid & 7) * 8;
;     const bf16_t* vt_src = P.Vt + (size_t)(h * 64 + (tid >> 3)) * VT_LD + kloc0 + (tid & 7) * 8;
;     const bf16_t* kr_src = P.KR + (size_t)(kglob0 + ((tid & 255) >> 2)) * 32 + (tid & 3) * 8;
;     const int k_w = (tid >> 3) * KP + (tid & 7) * 16, r_w = ((tid & 255) >> 2) * KP + 128 + (tid & 3) * 16;
.LBB0_1143:
	v_mov_b32_e32 v16, v167
	s_and_b64 s[38:39], s[66:67], exec
	s_cselect_b32 s68, s3, s25
	v_readfirstlane_b32 s69, v16
	s_ashr_i32 s39, s69, 1
	s_lshl_b32 s27, s68, 8
	s_and_b32 s64, s39, 0xffffffe0
	v_mov_b32_e32 v0, s39
	s_movk_i32 s39, 0xffe0
	s_or_b32 s38, s27, s8
	v_bfi_b32 v143, s39, v0, v16
	v_add_u32_e32 v0, s38, v143
	v_and_b32_e32 v17, 31, v16
	s_add_i32 s64, s64, s27
	v_ashrrev_i32_e32 v1, 31, v0
	v_bfe_u32 v142, v16, 5, 1
	v_or_b32_e32 v4, s64, v17
	v_lshlrev_b64 v[2:3], 11, v[0:1]
	v_lshlrev_b64 v[0:1], 10, v[0:1]
	v_lshl_add_u64 v[2:3], s[16:17], 0, v[2:3]
	v_lshl_add_u64 v[0:1], s[22:23], 0, v[0:1]
	v_lshlrev_b32_e32 v4, 5, v4
	v_lshlrev_b32_e32 v64, 4, v142
	v_ashrrev_i32_e32 v5, 31, v4
	v_lshl_add_u64 v[2:3], v[2:3], 0, v[64:65]
	v_lshl_add_u64 v[0:1], v[0:1], 0, v[64:65]
	v_lshl_add_u64 v[4:5], v[4:5], 2, s[14:15]
	global_load_dwordx4 v[78:81], v[2:3], off
	global_load_dwordx4 v[74:77], v[2:3], off offset:32
	global_load_dwordx4 v[70:73], v[2:3], off offset:64
	s_waitcnt lgkmcnt(0)
	global_load_dwordx4 v[66:69], v[2:3], off offset:96
	global_load_dwordx4 v[8:11], v[0:1], off
	global_load_dwordx4 v[12:15], v[0:1], off offset:32
	v_lshlrev_b32_e32 v0, 5, v142
	v_mov_b32_e32 v1, v65
	v_lshl_add_u64 v[22:23], v[4:5], 0, v[0:1]
	global_load_dwordx4 v[0:3], v[22:23], off offset:16
	global_load_dwordx4 v[18:21], v[22:23], off
	global_load_dwordx4 v[4:7], v[22:23], off offset:80
	s_nop 0
	global_load_dwordx4 v[22:25], v[22:23], off offset:64
	v_mov_b32_e32 v90, v65
	v_mov_b32_e32 v91, v65
	v_mov_b32_e32 v92, v65
	v_mov_b32_e32 v93, v65
	s_waitcnt vmcnt(5)
	v_lshlrev_b32_e32 v27, 16, v8
	s_waitcnt vmcnt(4)
	v_lshlrev_b32_e32 v26, 16, v12
	s_waitcnt vmcnt(2)
	v_mov_b32_e32 v29, v18
	s_waitcnt vmcnt(0)
	v_mov_b32_e32 v28, v22
	v_pk_mul_f32 v[28:29], v[28:29], v[26:27]
	s_nop 0
	v_sub_f32_e32 v30, v29, v28
	v_mov_b32_e32 v28, v18
	v_mov_b32_e32 v29, v22
	v_pk_mul_f32 v[26:27], v[28:29], v[26:27]
	v_mov_b32_e32 v18, v23
	v_add_f32_e32 v31, v26, v27
	v_and_b32_e32 v27, 0xffff0000, v8
	v_and_b32_e32 v26, 0xffff0000, v12
	v_mov_b32_e32 v22, v19
	v_pk_mul_f32 v[28:29], v[18:19], v[26:27]
	v_pk_mul_f32 v[18:19], v[22:23], v[26:27]
	v_mov_b32_e32 v22, v24
	v_add_f32_e32 v26, v18, v19
	v_lshlrev_b32_e32 v19, 16, v9
	v_lshlrev_b32_e32 v18, 16, v13
	v_mov_b32_e32 v23, v20
	v_pk_mul_f32 v[22:23], v[22:23], v[18:19]
	v_and_b32_e32 v9, 0xffff0000, v9
	v_sub_f32_e32 v27, v23, v22
	v_mov_b32_e32 v22, v20
	v_mov_b32_e32 v23, v24
	v_and_b32_e32 v8, 0xffff0000, v13
	v_mov_b32_e32 v20, v25
	v_mov_b32_e32 v24, v21
	v_pk_mul_f32 v[18:19], v[22:23], v[18:19]
	v_pk_mul_f32 v[12:13], v[20:21], v[8:9]
	v_pk_mul_f32 v[8:9], v[24:25], v[8:9]
	v_add_f32_e32 v18, v18, v19
	v_sub_f32_e32 v19, v13, v12
	v_add_f32_e32 v20, v8, v9
	v_lshlrev_b32_e32 v9, 16, v10
	v_lshlrev_b32_e32 v8, 16, v14
	v_mov_b32_e32 v12, v4
	v_mov_b32_e32 v13, v0
	v_pk_mul_f32 v[12:13], v[12:13], v[8:9]
	v_sub_f32_e32 v28, v29, v28
	v_sub_f32_e32 v21, v13, v12
	v_mov_b32_e32 v12, v0
	v_mov_b32_e32 v13, v4
	v_pk_mul_f32 v[8:9], v[12:13], v[8:9]
	v_mov_b32_e32 v0, v5
	v_add_f32_e32 v22, v8, v9
	v_and_b32_e32 v9, 0xffff0000, v10
	v_and_b32_e32 v8, 0xffff0000, v14
	v_mov_b32_e32 v4, v1
	v_pk_mul_f32 v[12:13], v[0:1], v[8:9]
	v_pk_mul_f32 v[0:1], v[4:5], v[8:9]
	v_mov_b32_e32 v4, v6
	v_add_f32_e32 v8, v0, v1
	v_lshlrev_b32_e32 v1, 16, v11
	v_lshlrev_b32_e32 v0, 16, v15
	v_mov_b32_e32 v5, v2
	v_pk_mul_f32 v[4:5], v[4:5], v[0:1]
	v_sub_f32_e32 v10, v13, v12
	v_sub_f32_e32 v9, v5, v4
	v_mov_b32_e32 v4, v2
	v_mov_b32_e32 v5, v6
	v_pk_mul_f32 v[0:1], v[4:5], v[0:1]
	v_mov_b32_e32 v2, v7
	v_add_f32_e32 v12, v0, v1
	v_and_b32_e32 v1, 0xffff0000, v11
	v_and_b32_e32 v0, 0xffff0000, v15
	v_mov_b32_e32 v6, v3
	v_pk_mul_f32 v[4:5], v[2:3], v[0:1]
	v_pk_mul_f32 v[0:1], v[6:7], v[0:1]
	v_sub_f32_e32 v2, v5, v4
	v_add_f32_e32 v0, v0, v1
	v_cvt_pk_bf16_f32 v86, v30, v28
	v_cvt_pk_bf16_f32 v87, v27, v19
	v_cvt_pk_bf16_f32 v88, v21, v10
	v_cvt_pk_bf16_f32 v89, v9, v2
	v_cvt_pk_bf16_f32 v82, v31, v26
	v_cvt_pk_bf16_f32 v83, v18, v20
	v_cvt_pk_bf16_f32 v84, v22, v8
	v_cvt_pk_bf16_f32 v85, v12, v0
	v_ashrrev_i32_e32 v12, 3, v16
	v_add_u32_e32 v0, s8, v12
	v_ashrrev_i32_e32 v1, 31, v0
	v_and_b32_e32 v2, 7, v16
	v_lshlrev_b64 v[0:1], 11, v[0:1]
	v_lshlrev_b32_e32 v8, 4, v2
	v_add_u32_e32 v4, s26, v12
	v_mov_b64_e32 v[2:3], s[30:31]
	v_lshl_add_u64 v[0:1], s[28:29], 0, v[0:1]
	v_mov_b32_e32 v9, v65
	v_mad_i64_i32 v[2:3], s[38:39], v4, s77, v[2:3]
	v_lshl_add_u64 v[0:1], v[0:1], 0, v[8:9]
	v_lshl_add_u64 v[2:3], v[2:3], 0, v[8:9]
	v_add_co_u32_e32 v98, vcc, 0x20000, v0
	s_nop 1
	v_addc_co_u32_e32 v99, vcc, 0, v1, vcc
	v_add_co_u32_e32 v180, vcc, 0x40000, v0
	s_nop 1
	v_addc_co_u32_e32 v181, vcc, 0, v1, vcc
	v_lshl_add_u64 v[94:95], v[2:3], 0, s[44:45]
	v_lshl_add_u64 v[176:177], v[94:95], 0, s[44:45]
	global_load_dwordx4 v[4:7], v[0:1], off
	s_nop 0
	global_load_dwordx4 v[0:3], v[2:3], off
	s_movk_i32 s38, 0xff
	v_and_b32_e32 v9, 3, v16
	v_cmp_lt_i32_e32 vcc, s38, v16
	s_movk_i32 s38, 0x100
	v_bfe_u32 v13, v16, 2, 6
	v_cmp_gt_i32_e64 s[38:39], s38, v16
	v_lshlrev_b32_e32 v10, 4, v9
	s_and_saveexec_b64 s[64:65], s[38:39]
	s_cbranch_execz .LBB0_1145
	v_or_b32_e32 v14, s24, v13
	v_ashrrev_i32_e32 v15, 31, v14
	v_lshlrev_b64 v[14:15], 6, v[14:15]
	v_lshl_add_u64 v[14:15], s[12:13], 0, v[14:15]
	v_mov_b32_e32 v11, v65
	v_lshl_add_u64 v[14:15], v[14:15], 0, v[10:11]
	global_load_dwordx4 v[102:105], v[14:15], off
	v_lshl_add_u64 v[14:15], v[14:15], 0, s[34:35]
	global_load_dwordx4 v[90:93], v[14:15], off
	v_lshl_add_u64 v[14:15], v[14:15], 0, s[34:35]
	global_load_dwordx4 v[172:175], v[14:15], off
